# scan prep split between waves 4-5 (decay) and 6-7 (store + a/k/r/v), on top of pipelined recurrence loop and hoisted parameter loads
# baseline (speedup 1.0000x reference)
; DI void rwkv_scan_item(int j, int item, LAS unsigned char* lds) {
;     ...
;     const int b = item >> 5, head = (item >> 1) & 15, d = item & 1;
;     LAS float* steps = (LAS float*)lds;
;     LAS bf16_t* L1w = (LAS bf16_t*)(lds + 98304);
;     LAS bf16_t* W2w = (LAS bf16_t*)(lds + 107008);
;     LAS bf16_t* W2a = (LAS bf16_t*)(lds + 116224);
;     LAS float* ybuf = (LAS float*)(lds + 125440);
;     const bf16_t* R = (const bf16_t*)(ws + OD_RKV); const bf16_t* Kb = R + (size_t)M * D; const bf16_t* Vb = Kb + (size_t)M * D;
;     const bf16_t* L1 = (const bf16_t*)(ws + OD_L1);
;     bf16_t* Y = (bf16_t*)(ws + OD_Y) + (size_t)d * M * D; float* SB = (float*)(ws + OD_SB) + (size_t)d * M * 16;
;     constexpr int NC = T / 32;
;     __syncthreads();
;     { const int n = tid >> 3, kc = tid & 7;
;       const bf16_t* sw = (const bf16_t*)(ws + W_2W_T) + ((size_t)(j * 2 + d) * D + head * 64 + n) * 64 + kc * 8;
;       const bf16_t* sa = (const bf16_t*)(ws + W_2A_T) + ((size_t)(j * 2 + d) * D + head * 64 + n) * 64 + kc * 8;
;       *(LAS u32x4*)(W2w + n * 72 + kc * 8) = *(const u32x4*)sw; *(LAS u32x4*)(W2a + n * 72 + kc * 8) = *(const u32x4*)sa; }
;     __syncthreads();
;     const int rp = (tid >> 3) & 31, cg8 = tid & 7;
;     f32x4 s0a = (f32x4){0.f, 0.f, 0.f, 0.f}, s0b = s0a, s1a = s0a, s1b = s0a;
;     ...
;                 const float* w0 = IN(20) + (size_t)(j * 2 + d) * D + head * 64; const float* a0 = IN(23) + (size_t)(j * 2 + d) * D + head * 64;
;                 { f32x4 acc[4];
; #pragma unroll
;                   for (int i = 0; i < 4; ++i) acc[i] = (f32x4){0.f, 0.f, 0.f, 0.f};
;                   mm16<4, 2>(Lw, 136, W2w, 72, acc, fr, fq);
; #pragma unroll
;                   for (int nt = 0; nt < 4; ++nt) { const int ch = nt * 16 + fq * 4; f32x4 o;
; #pragma unroll
;                       for (int e = 0; e < 4; ++e) { const float wp = w0[ch + e] + acc[nt][e]; const float wl = -__logf(1.f + __expf(-wp)) - 0.5f; o[e] = __expf(-__expf(wl)); }
;                       *(LAS f32x4*)(sbuf + (r0 + fr) * 384 + ch) = o; } }
;                 { f32x4 acc[4];
; #pragma unroll
;                   for (int i = 0; i < 4; ++i) acc[i] = (f32x4){0.f, 0.f, 0.f, 0.f};
;                   mm16<4, 2>(Lw + 64, 136, W2a, 72, acc, fr, fq);
; #pragma unroll
;                   for (int nt = 0; nt < 4; ++nt) { const int ch = nt * 16 + fq * 4; f32x4 o;
; #pragma unroll
.LBB0_108:
	v_readlane_b32 s2, v255, 17
	v_readlane_b32 s3, v255, 18
	s_load_dwordx2 s[4:5], s[2:3], 0x118
	s_waitcnt vmcnt(0)
	v_mov_b32_e32 v4, v182
	s_and_b32 s16, s22, 1
	v_readfirstlane_b32 s2, v4
	s_ashr_i32 s24, s2, 6
	s_mul_i32 s2, s16, 0x8800
	s_waitcnt lgkmcnt(0)
	s_ashr_i32 s12, s22, 5
	s_bfe_u32 s15, s22, 0x40001
	s_lshl_b32 s3, s2, 11
	s_waitcnt lgkmcnt(0)
	s_add_u32 s18, s4, s3
	s_addc_u32 s19, s5, 0
	s_lshl_b32 s2, s2, 6
	s_add_u32 s17, s4, s2
	s_addc_u32 s14, s5, 0
	s_lshl_b32 s2, s16, 10
	v_ashrrev_i32_e32 v2, 3, v4
	s_or_b32 s2, s2, s20
	s_lshl_b32 s3, s15, 6
	s_or_b32 s80, s2, s3
	v_ashrrev_i32_e32 v3, 31, v2
	v_lshl_add_u64 v[6:7], s[80:81], 0, v[2:3]
	v_lshlrev_b64 v[6:7], 7, v[6:7]
	v_lshlrev_b32_e32 v14, 4, v4
	v_and_b32_e32 v0, 0x70, v14
	v_lshl_add_u64 v[6:7], s[4:5], 0, v[6:7]
	v_lshl_add_u64 v[10:11], v[6:7], 0, v[0:1]
	s_mov_b32 s6, 0x6d00000
	v_add_co_u32_e32 v6, vcc, s6, v10
	s_waitcnt vmcnt(0)
	s_nop 0
	v_addc_co_u32_e32 v7, vcc, 0, v11, vcc
	s_barrier
	global_load_dwordx4 v[6:9], v[6:7], off
	s_movk_i32 s6, 0x90
	v_mad_u64_u32 v[12:13], s[6:7], v2, s6, v[0:1]
	v_add_u32_e32 v0, 0x1a210, v12
	s_mov_b32 s6, 0x6d80000
	s_cmp_gt_i32 s24, 3
	v_and_b32_e32 v5, 15, v4
	v_bfe_u32 v43, v4, 4, 2
	v_lshlrev_b32_e32 v3, 3, v4
	v_and_b32_e32 v3, 64, v3
	v_lshl_add_u32 v3, s16, 6, v3
	v_lshlrev_b32_e32 v42, 2, v5
	v_cmp_eq_u32_e64 s[42:43], 0, v5
	s_mul_hi_i32 s13, s12, 0x1100
	s_mulk_i32 s12, 0x1100
	v_or_b32_e32 v92, 4, v43
	v_or_b32_e32 v93, 8, v43
	v_or_b32_e32 v94, 12, v43
	s_waitcnt vmcnt(0)
	ds_write_b128 v0, v[6:9]
	v_add_co_u32_e32 v6, vcc, s6, v10
	s_cselect_b64 s[6:7], -1, 0
	s_nop 0
	v_addc_co_u32_e32 v7, vcc, 0, v11, vcc
	global_load_dwordx4 v[6:9], v[6:7], off
	s_cmp_gt_u32 s24, 5
	s_cselect_b64 s[10:11], -1, 0
	s_lshl_b32 s23, s24, 4
	s_cmp_eq_u32 s16, 0
	v_add_u32_e32 v0, 0x1c610, v12
	s_cselect_b64 s[40:41], -1, 0
	s_lshl_b32 s25, s15, 7
	s_add_u32 s18, s18, s25
	s_addc_u32 s19, s19, 0
	v_mul_u32_u24_e32 v11, 0x90, v5
	s_waitcnt vmcnt(0)
	ds_write_b128 v0, v[6:9]
	v_mov_b32_e32 v0, 0x1ea10
	v_lshl_add_u32 v81, v5, 4, v0
	v_lshlrev_b32_e32 v0, 3, v5
	v_lshl_add_u64 v[6:7], s[18:19], 0, v[0:1]
	s_mov_b64 s[18:19], 0x7000000
	v_lshl_add_u64 v[44:45], v[6:7], 0, s[18:19]
	s_mul_i32 s18, s24, 0x1100
	v_or_b32_e32 v8, s23, v43
	s_sub_i32 s23, s23, 64
	s_add_i32 s24, s18, 0x13c10
	s_and_b64 s[26:27], s[10:11], exec
	s_cselect_b32 s26, 0x8800, 0
	s_cselect_b32 s27, 32, 0
	s_add_i32 s24, s24, s26
	s_sub_i32 s23, s23, s27
	s_add_u32 s18, s4, s25
	s_addc_u32 s19, s5, 0
	v_lshl_add_u64 v[6:7], s[18:19], 0, v[0:1]
	s_mov_b64 s[18:19], 0x13c00000
	v_lshl_add_u64 v[46:47], v[6:7], 0, s[18:19]
	s_mov_b64 s[18:19], 0xf800000
	v_lshl_add_u64 v[48:49], v[6:7], 0, s[18:19]
	s_mov_b64 s[18:19], 0x18000000
	v_lshl_add_u64 v[50:51], v[6:7], 0, s[18:19]
	v_and_b32_e32 v6, 0xf0, v14
	v_add_u32_e32 v7, s24, v6
	v_mul_u32_u24_e32 v6, 0x110, v5
	v_lshlrev_b32_e32 v9, 4, v43
	v_or_b32_e32 v12, s23, v5
	s_movk_i32 s19, 0x600
	v_add_lshl_u32 v0, v3, v0, 1
	v_add_u32_e32 v80, 0xffffffa0, v8
	v_add3_u32 v83, s24, v6, v9
	v_add_u32_e32 v10, 0x1a210, v9
	v_mul_lo_u32 v84, v12, s19
	v_add_u32_e32 v12, 0x1c610, v9
	s_or_b32 s18, s3, s21
	s_lshl_b32 s15, s15, 2
	v_add_u32_e32 v86, 0xffffffa4, v8
	v_add_u32_e32 v88, 0xffffffa8, v8
	v_add_u32_e32 v90, 0xffffffac, v8
	v_lshl_add_u64 v[8:9], s[4:5], 0, v[0:1]
	v_lshlrev_b32_e32 v0, 2, v2
	s_add_u32 s15, s17, s15
	v_and_b32_e32 v0, 0x7c, v0
	v_or_b32_e32 v82, s23, v43
	v_lshlrev_b32_e32 v6, 2, v43
	s_addc_u32 s17, s14, 0
	s_mov_b64 s[4:5], 0x1c400000
	v_mul_u32_u24_e32 v5, 0x110, v43
	v_add_u32_e32 v102, 0x1ea10, v0
	v_add_u32_e32 v103, 0x510, v0
	v_and_b32_e32 v0, 7, v4
	v_mov_b32_e32 v2, v1
	v_mov_b32_e32 v3, v1
	s_add_u32 s14, s15, 0x1e600000
	v_lshl_add_u64 v[52:53], v[8:9], 0, s[4:5]
	v_mul_lo_u32 v95, v82, s19
	v_lshl_or_b32 v104, v0, 5, 16
	v_mov_b32_e32 v0, v1
	v_add_u32_e32 v105, v7, v5
	v_add_u32_e32 v106, v10, v11
	v_lshlrev_b32_e32 v107, 2, v6
	v_add_u32_e32 v108, v12, v11
	v_mov_b64_e32 v[6:7], v[2:3]
	v_mov_b64_e32 v[10:11], v[2:3]
	v_mov_b64_e32 v[14:15], v[2:3]
	v_mov_b64_e32 v[18:19], v[2:3]
	s_addc_u32 s15, s17, 0
	v_lshlrev_b32_e32 v85, 8, v80
	v_lshlrev_b32_e32 v87, 8, v86
	v_lshlrev_b32_e32 v89, 8, v88
	v_lshlrev_b32_e32 v91, 8, v90
	v_or_b32_e32 v96, 4, v82
	v_add_u32_e32 v97, 0x1800, v95
	v_or_b32_e32 v98, 8, v82
	v_add_u32_e32 v99, 0x3000, v95
	v_or_b32_e32 v100, 12, v82
	v_add_u32_e32 v101, 0x4800, v95
	s_mov_b32 s24, -1
	s_mov_b64 s[16:17], -1
	s_lshl_b32 s25, s2, 2
	s_lshl_b32 s28, s3, 2
	s_lshl_b32 s29, s18, 2
	v_mov_b64_e32 v[4:5], v[0:1]
	v_mov_b64_e32 v[8:9], v[0:1]
	v_mov_b64_e32 v[12:13], v[0:1]
	v_mov_b64_e32 v[16:17], v[0:1]
	v_readlane_b32 s36, v255, 17
	v_readlane_b32 s37, v255, 18
	s_lshl_b32 s38, s21, 2
	s_nop 3
	s_load_dwordx2 s[2:3], s[36:37], 0xa0
	s_load_dwordx2 s[4:5], s[36:37], 0xb8
	s_load_dwordx2 s[18:19], s[36:37], 0xe0
	s_load_dwordx2 s[26:27], s[36:37], 0xe8
	s_load_dwordx2 s[34:35], s[36:37], 0xf0
	v_lshlrev_b32_e32 v124, 2, v42
	s_waitcnt lgkmcnt(0)
	s_add_u32 s2, s2, s25
	s_addc_u32 s3, s3, 0
	s_add_u32 s2, s2, s28
	s_addc_u32 s3, s3, 0
	s_add_u32 s4, s4, s25
	s_addc_u32 s5, s5, 0
	s_add_u32 s4, s4, s28
	s_addc_u32 s5, s5, 0
	s_add_u32 s18, s18, s38
	s_addc_u32 s19, s19, 0
	s_add_u32 s18, s18, s28
	s_addc_u32 s19, s19, 0
	s_add_u32 s26, s26, s38
	s_addc_u32 s27, s27, 0
	s_add_u32 s26, s26, s28
	s_addc_u32 s27, s27, 0
	s_add_u32 s34, s34, s29
	s_addc_u32 s35, s35, 0
	global_load_dwordx4 v[140:143], v107, s[2:3]
	global_load_dwordx4 v[144:147], v107, s[2:3] offset:64
	global_load_dwordx4 v[148:151], v107, s[2:3] offset:128
	global_load_dwordx4 v[152:155], v107, s[2:3] offset:192
	global_load_dwordx4 v[156:159], v107, s[4:5]
	global_load_dwordx4 v[160:163], v107, s[4:5] offset:64
	global_load_dwordx4 v[164:167], v107, s[4:5] offset:128
	global_load_dwordx4 v[168:171], v107, s[4:5] offset:192
	global_load_dwordx4 v[172:175], v124, s[18:19]
	global_load_dwordx4 v[176:179], v124, s[26:27]
	global_load_dwordx4 v[120:123], v124, s[34:35]
	s_waitcnt vmcnt(0)
	s_waitcnt lgkmcnt(0)
	s_barrier
	s_branch .LBB0_110

; #define LAS __attribute__((address_space(3)))
; DI int tok_of(int d, int i) { if (i < LC) return d ? (LC - 1 - i) : i; return d ? (LC + SL - 1 - (i - LC)) : i; }
; DI void rwkv_scan_item(int j, int item, LAS unsigned char* lds) {
;     ...
;             const int cn = c + 1;
;             if (cn < NC) {
;                 const int pw = wave - 4, r0 = pw * 16, i0 = cn * 32;
;                 LAS float* sbuf = steps + (cn & 1) * 12288; LAS bf16_t* Lw = L1w + pw * 16 * 136;
;                 u32x4 l1v[4]; u32x2 kv[4], rv[4], vv[4];
; #pragma unroll
;                 for (int i = 0; i < 4; ++i) { const int q = lane + 64 * i; const int row = q >> 4, cc = q & 15; const int sc = cc < 8 ? d * 64 + cc * 8 : 128 + d * 64 + (cc - 8) * 8;
;                     const size_t mr = (size_t)b * T + tok_of(d, i0 + r0 + row);
;                     l1v[i] = *(const u32x4*)(L1 + mr * 256 + sc); }
; #pragma unroll
;                 for (int i = 0; i < 4; ++i) { const int row = i * 4 + fq; const size_t mr = (size_t)b * T + tok_of(d, i0 + r0 + row);
;                     kv[i] = *(const u32x2*)(Kb + mr * D + head * 64 + fr * 4); rv[i] = *(const u32x2*)(R + mr * D + head * 64 + fr * 4); vv[i] = *(const u32x2*)(Vb + mr * D + head * 64 + fr * 4); }
; #pragma unroll
;                 for (int i = 0; i < 4; ++i) { const int q = lane + 64 * i; *(LAS u32x4*)(Lw + (q >> 4) * 136 + (q & 15) * 8) = l1v[i]; }
;                 asm volatile("s_waitcnt lgkmcnt(0)" ::: "memory");
.LBB0_114:
	s_mov_b64 s[2:3], -1
.LBB0_115:
	s_andn2_b64 vcc, exec, s[2:3]
	s_cbranch_vccnz .LBB0_126
	s_cmpk_gt_i32 s24, 0x86
	s_cbranch_scc1 .LBB0_126
	s_add_i32 s2, s24, 1
	s_lshl_b32 s34, s2, 5
	s_bitcmp1_b32 s2, 0
	s_cselect_b32 s35, 0xc010, 16
	s_add_i32 s2, s34, s23
	v_or_b32_e32 v0, s2, v43
	s_movk_i32 s3, 0xff
	v_cmp_lt_i32_e32 vcc, s3, v0
	v_readlane_b32 s36, v255, 17
	v_readlane_b32 s37, v255, 18
	v_cndmask_b32_e32 v2, v253, v196, vcc
	v_sub_u32_e32 v2, v2, v0
	v_cndmask_b32_e64 v2, v2, v0, s[40:41]
	v_ashrrev_i32_e32 v3, 31, v2
	v_lshl_add_u64 v[2:3], s[12:13], 0, v[2:3]
	v_lshlrev_b64 v[2:3], 9, v[2:3]
	v_or_b32_e32 v0, s2, v92
	v_lshl_add_u64 v[2:3], v[52:53], 0, v[2:3]
	v_cmp_lt_i32_e32 vcc, s3, v0
	global_load_dwordx4 v[20:23], v[2:3], off
	s_mov_b32 s26, 0x800000
	v_cndmask_b32_e32 v2, v253, v196, vcc
	v_sub_u32_e32 v2, v2, v0
	v_cndmask_b32_e64 v2, v2, v0, s[40:41]
	v_ashrrev_i32_e32 v3, 31, v2
	v_lshl_add_u64 v[2:3], s[12:13], 0, v[2:3]
	v_lshlrev_b64 v[2:3], 9, v[2:3]
	v_or_b32_e32 v0, s2, v93
	v_lshl_add_u64 v[2:3], v[52:53], 0, v[2:3]
	v_cmp_lt_i32_e32 vcc, s3, v0
	global_load_dwordx4 v[24:27], v[2:3], off
	s_mov_b32 s27, 0x3f317217
	v_cndmask_b32_e32 v2, v253, v196, vcc
	v_sub_u32_e32 v2, v2, v0
	v_cndmask_b32_e64 v2, v2, v0, s[40:41]
	v_ashrrev_i32_e32 v3, 31, v2
	v_lshl_add_u64 v[2:3], s[12:13], 0, v[2:3]
	v_lshlrev_b64 v[2:3], 9, v[2:3]
	v_or_b32_e32 v0, s2, v94
	v_lshl_add_u64 v[2:3], v[52:53], 0, v[2:3]
	v_cmp_lt_i32_e32 vcc, s3, v0
	global_load_dwordx4 v[28:31], v[2:3], off
	s_mov_b32 s38, 0x7f800000
	v_cndmask_b32_e32 v2, v253, v196, vcc
	v_sub_u32_e32 v2, v2, v0
	v_cndmask_b32_e64 v2, v2, v0, s[40:41]
	v_ashrrev_i32_e32 v3, 31, v2
	v_lshl_add_u64 v[2:3], s[12:13], 0, v[2:3]
	v_lshlrev_b64 v[2:3], 9, v[2:3]
	v_lshl_add_u64 v[2:3], v[52:53], 0, v[2:3]
	global_load_dwordx4 v[32:35], v[2:3], off
	v_add_u32_e32 v0, s34, v82
	v_cmp_lt_i32_e32 vcc, s3, v0
	s_nop 1
	v_cndmask_b32_e32 v2, v253, v196, vcc
	v_sub_u32_e32 v2, v2, v0
	v_cndmask_b32_e64 v2, v2, v0, s[40:41]
	v_ashrrev_i32_e32 v3, 31, v2
	v_lshl_add_u64 v[66:67], s[12:13], 0, v[2:3]
	v_lshlrev_b64 v[2:3], 11, v[66:67]
	v_lshl_add_u64 v[36:37], v[46:47], 0, v[2:3]
	global_load_dwordx2 v[72:73], v[36:37], off
	v_lshl_add_u64 v[36:37], v[48:49], 0, v[2:3]
	v_lshl_add_u64 v[2:3], v[50:51], 0, v[2:3]
	global_load_dwordx2 v[36:37], v[36:37], off
	s_nop 0
	global_load_dwordx2 v[40:41], v[2:3], off
	v_or_b32_e32 v2, 4, v0
	v_cmp_lt_i32_e32 vcc, s3, v2
	s_nop 1
	v_cndmask_b32_e32 v3, v253, v196, vcc
	v_sub_u32_e32 v3, v3, v2
	v_cndmask_b32_e64 v2, v3, v2, s[40:41]
	v_ashrrev_i32_e32 v3, 31, v2
	v_lshl_add_u64 v[2:3], s[12:13], 0, v[2:3]
	v_lshlrev_b64 v[2:3], 11, v[2:3]
	v_lshl_add_u64 v[38:39], v[46:47], 0, v[2:3]
	global_load_dwordx2 v[64:65], v[38:39], off
	v_lshl_add_u64 v[38:39], v[48:49], 0, v[2:3]
	v_lshl_add_u64 v[2:3], v[50:51], 0, v[2:3]
	global_load_dwordx2 v[68:69], v[38:39], off
	global_load_dwordx2 v[70:71], v[2:3], off
	v_or_b32_e32 v2, 8, v0
	v_cmp_lt_i32_e32 vcc, s3, v2
	v_or_b32_e32 v0, 12, v0
	s_nop 0
	v_cndmask_b32_e32 v3, v253, v196, vcc
	v_sub_u32_e32 v3, v3, v2
	v_cndmask_b32_e64 v2, v3, v2, s[40:41]
	v_ashrrev_i32_e32 v3, 31, v2
	v_lshl_add_u64 v[2:3], s[12:13], 0, v[2:3]
	v_lshlrev_b64 v[2:3], 11, v[2:3]
	v_lshl_add_u64 v[38:39], v[46:47], 0, v[2:3]
	global_load_dwordx2 v[58:59], v[38:39], off
	v_lshl_add_u64 v[38:39], v[48:49], 0, v[2:3]
	v_lshl_add_u64 v[2:3], v[50:51], 0, v[2:3]
	v_cmp_lt_i32_e32 vcc, s3, v0
	global_load_dwordx2 v[62:63], v[38:39], off
	global_load_dwordx2 v[60:61], v[2:3], off
	v_cndmask_b32_e32 v2, v253, v196, vcc
	v_sub_u32_e32 v2, v2, v0
	v_cndmask_b32_e64 v2, v2, v0, s[40:41]
	v_ashrrev_i32_e32 v3, 31, v2
	v_lshl_add_u64 v[2:3], s[12:13], 0, v[2:3]
	v_lshlrev_b64 v[38:39], 11, v[2:3]
	v_lshl_add_u64 v[2:3], v[46:47], 0, v[38:39]
	v_lshl_add_u64 v[54:55], v[48:49], 0, v[38:39]
	v_lshl_add_u64 v[38:39], v[50:51], 0, v[38:39]
	global_load_dwordx2 v[2:3], v[2:3], off
	s_mov_b64 s[2:3], s[36:37]
	global_load_dwordx2 v[54:55], v[54:55], off
	s_nop 0
	global_load_dwordx2 v[56:57], v[38:39], off
	s_waitcnt vmcnt(15)
	ds_write_b128 v105, v[20:23]
	s_waitcnt vmcnt(14)
	ds_write_b128 v105, v[24:27] offset:1088
	s_waitcnt vmcnt(13)
	ds_write_b128 v105, v[28:31] offset:2176
	s_waitcnt vmcnt(12)
	ds_write_b128 v105, v[32:35] offset:3264
	s_waitcnt lgkmcnt(0)
	s_and_b64 vcc, exec, s[10:11]
	s_cbranch_vccnz .Lprep_af
; #define LAS __attribute__((address_space(3)))
; #define IN(k) ((const float*)kload(8 * (k)))
; DI void rwkv_scan_item(int j, int item, LAS unsigned char* lds) {
;     ...
;                 const float* w0 = IN(20) + (size_t)(j * 2 + d) * D + head * 64; const float* a0 = IN(23) + (size_t)(j * 2 + d) * D + head * 64;
;                 { f32x4 acc[4];
; #pragma unroll
;                   for (int i = 0; i < 4; ++i) acc[i] = (f32x4){0.f, 0.f, 0.f, 0.f};
;                   mm16<4, 2>(Lw, 136, W2w, 72, acc, fr, fq);
; #pragma unroll
;                   for (int nt = 0; nt < 4; ++nt) { const int ch = nt * 16 + fq * 4; f32x4 o;
; #pragma unroll
;                       for (int e = 0; e < 4; ++e) { const float wp = w0[ch + e] + acc[nt][e]; const float wl = -__logf(1.f + __expf(-wp)) - 0.5f; o[e] = __expf(-__expf(wl)); }
;                       *(LAS f32x4*)(sbuf + (r0 + fr) * 384 + ch) = o; } }
	s_waitcnt lgkmcnt(0)
	s_add_u32 s4, s2, s25
	s_addc_u32 s5, s3, 0
	s_mov_b64 s[2:3], s[36:37]
	ds_read_b128 v[20:23], v83
	ds_read_b128 v[24:27], v106
	ds_read_b128 v[28:31], v106 offset:2304
	ds_read_b128 v[32:35], v106 offset:4608
	ds_read_b128 v[74:77], v106 offset:6912
	s_waitcnt lgkmcnt(0)
	v_mfma_f32_16x16x32_bf16 v[24:27], v[24:27], v[20:23], 0
	s_add_u32 s2, s2, s25
	s_addc_u32 s3, s3, 0
	s_add_u32 s18, s4, s28
	v_mfma_f32_16x16x32_bf16 v[28:31], v[28:31], v[20:23], 0
	s_addc_u32 s19, s5, 0
	v_mfma_f32_16x16x32_bf16 v[32:35], v[32:35], v[20:23], 0
	v_mfma_f32_16x16x32_bf16 v[20:23], v[74:77], v[20:23], 0
	ds_read_b128 v[74:77], v83 offset:64
	ds_read_b128 v[110:113], v106 offset:64
	s_waitcnt lgkmcnt(0)
	v_mfma_f32_16x16x32_bf16 v[110:113], v[110:113], v[74:77], v[24:27]
	s_nop 2
	ds_read_b128 v[24:27], v106 offset:2368
	s_waitcnt lgkmcnt(0)
	v_mfma_f32_16x16x32_bf16 v[28:31], v[24:27], v[74:77], v[28:31]
	ds_read_b128 v[24:27], v106 offset:4672
	s_waitcnt lgkmcnt(0)
	v_mfma_f32_16x16x32_bf16 v[24:27], v[24:27], v[74:77], v[32:35]
	s_nop 2
	ds_read_b128 v[32:35], v106 offset:6976
	s_waitcnt lgkmcnt(0)
	v_mfma_f32_16x16x32_bf16 v[20:23], v[32:35], v[74:77], v[20:23]
	v_mov_b64_e32 v[32:33], v[140:141]
	v_mov_b64_e32 v[34:35], v[142:143]
	s_waitcnt vmcnt(0)
	v_add_f32_e32 v0, v110, v32
	v_mul_f32_e32 v0, 0xbfb8aa3b, v0
	v_exp_f32_e32 v0, v0
	s_nop 0
	v_add_f32_e32 v0, 1.0, v0
	v_cmp_gt_f32_e32 vcc, s26, v0
	s_nop 1
	v_cndmask_b32_e64 v32, 0, 32, vcc
	v_ldexp_f32 v0, v0, v32
	v_log_f32_e32 v0, v0
	s_nop 0
	v_mul_f32_e32 v32, 0x3f317217, v0
	v_fma_f32 v32, v0, s27, -v32
	v_fmac_f32_e32 v32, 0x3377d1cf, v0
	v_fmac_f32_e32 v32, 0x3f317217, v0
	v_cmp_lt_f32_e64 s[4:5], |v0|, s38
	s_nop 1
	v_cndmask_b32_e64 v0, v0, v32, s[4:5]
	v_cndmask_b32_e32 v32, 0, v252, vcc
	v_sub_f32_e32 v0, v0, v32
	v_sub_f32_e32 v0, -0.5, v0
	v_mul_f32_e32 v0, 0x3fb8aa3b, v0
	v_exp_f32_e32 v0, v0
	s_nop 0
	v_mul_f32_e32 v0, 0xbfb8aa3b, v0
	v_exp_f32_e32 v32, v0
	v_add_f32_e32 v0, v111, v33
	v_mul_f32_e32 v0, 0xbfb8aa3b, v0
	v_exp_f32_e32 v0, v0
	s_nop 0
	v_add_f32_e32 v0, 1.0, v0
	v_cmp_gt_f32_e32 vcc, s26, v0
	s_nop 1
	v_cndmask_b32_e64 v33, 0, 32, vcc
	v_ldexp_f32 v0, v0, v33
	v_log_f32_e32 v0, v0
	s_nop 0
	v_mul_f32_e32 v33, 0x3f317217, v0
	v_fma_f32 v33, v0, s27, -v33
	v_fmac_f32_e32 v33, 0x3377d1cf, v0
	v_fmac_f32_e32 v33, 0x3f317217, v0
	v_cmp_lt_f32_e64 s[4:5], |v0|, s38
	s_nop 1
	v_cndmask_b32_e64 v0, v0, v33, s[4:5]
	v_cndmask_b32_e32 v33, 0, v252, vcc
	v_sub_f32_e32 v0, v0, v33
	v_sub_f32_e32 v0, -0.5, v0
	v_mul_f32_e32 v0, 0x3fb8aa3b, v0
	v_exp_f32_e32 v0, v0
	s_nop 0
	v_mul_f32_e32 v0, 0xbfb8aa3b, v0
	v_exp_f32_e32 v33, v0
	v_add_f32_e32 v0, v112, v34
	v_mul_f32_e32 v0, 0xbfb8aa3b, v0
	v_exp_f32_e32 v0, v0
	s_nop 0
	v_add_f32_e32 v0, 1.0, v0
	v_cmp_gt_f32_e32 vcc, s26, v0
	s_nop 1
	v_cndmask_b32_e64 v34, 0, 32, vcc
	v_ldexp_f32 v0, v0, v34
	v_log_f32_e32 v0, v0
	s_nop 0
	v_mul_f32_e32 v34, 0x3f317217, v0
	v_fma_f32 v34, v0, s27, -v34
	v_fmac_f32_e32 v34, 0x3377d1cf, v0
	v_fmac_f32_e32 v34, 0x3f317217, v0
	v_cmp_lt_f32_e64 s[4:5], |v0|, s38
	s_nop 1
	v_cndmask_b32_e64 v0, v0, v34, s[4:5]
	v_cndmask_b32_e32 v34, 0, v252, vcc
	v_sub_f32_e32 v0, v0, v34
	v_sub_f32_e32 v0, -0.5, v0
	v_mul_f32_e32 v0, 0x3fb8aa3b, v0
	v_exp_f32_e32 v0, v0
	s_nop 0
	v_mul_f32_e32 v0, 0xbfb8aa3b, v0
	v_exp_f32_e32 v34, v0
	v_add_f32_e32 v0, v113, v35
	v_mul_f32_e32 v0, 0xbfb8aa3b, v0
	v_exp_f32_e32 v0, v0
	s_nop 0
	v_add_f32_e32 v0, 1.0, v0
	v_cmp_gt_f32_e32 vcc, s26, v0
	s_nop 1
	v_cndmask_b32_e64 v35, 0, 32, vcc
	v_ldexp_f32 v0, v0, v35
	v_log_f32_e32 v0, v0
	s_nop 0
	v_mul_f32_e32 v35, 0x3f317217, v0
	v_fma_f32 v35, v0, s27, -v35
	v_fmac_f32_e32 v35, 0x3377d1cf, v0
	v_fmac_f32_e32 v35, 0x3f317217, v0
	v_cmp_lt_f32_e64 s[4:5], |v0|, s38
	s_nop 1
	v_cndmask_b32_e64 v0, v0, v35, s[4:5]
	v_cndmask_b32_e32 v35, 0, v252, vcc
	v_sub_f32_e32 v0, v0, v35
	v_sub_f32_e32 v0, -0.5, v0
	v_mul_f32_e32 v0, 0x3fb8aa3b, v0
	v_exp_f32_e32 v0, v0
	s_nop 0
	v_mul_f32_e32 v0, 0xbfb8aa3b, v0
	v_exp_f32_e32 v35, v0
	v_add3_u32 v0, s35, v84, v107
	ds_write_b128 v0, v[32:35]
	v_mov_b64_e32 v[32:33], v[144:145]
	v_mov_b64_e32 v[34:35], v[146:147]
	s_waitcnt vmcnt(0)
	v_add_f32_e32 v28, v28, v32
	v_mul_f32_e32 v28, 0xbfb8aa3b, v28
	v_exp_f32_e32 v28, v28
	v_add_f32_e32 v29, v29, v33
	v_mul_f32_e32 v29, 0xbfb8aa3b, v29
	v_exp_f32_e32 v29, v29
	v_add_f32_e32 v28, 1.0, v28
	v_cmp_gt_f32_e32 vcc, s26, v28
	v_add_f32_e32 v30, v30, v34
	v_add_f32_e32 v29, 1.0, v29
	v_cndmask_b32_e64 v32, 0, 32, vcc
	v_ldexp_f32 v28, v28, v32
	v_log_f32_e32 v28, v28
	v_mul_f32_e32 v30, 0xbfb8aa3b, v30
	v_exp_f32_e32 v30, v30
	v_add_f32_e32 v31, v31, v35
	v_mul_f32_e32 v32, 0x3f317217, v28
	v_fma_f32 v32, v28, s27, -v32
	v_fmac_f32_e32 v32, 0x3377d1cf, v28
	v_fmac_f32_e32 v32, 0x3f317217, v28
	v_cmp_lt_f32_e64 s[4:5], |v28|, s38
	v_add_f32_e32 v30, 1.0, v30
	v_mul_f32_e32 v31, 0xbfb8aa3b, v31
	v_cndmask_b32_e64 v28, v28, v32, s[4:5]
	v_cndmask_b32_e32 v32, 0, v252, vcc
	v_cmp_gt_f32_e32 vcc, s26, v29
	v_sub_f32_e32 v28, v28, v32
	v_exp_f32_e32 v31, v31
	v_cndmask_b32_e64 v32, 0, 32, vcc
	v_ldexp_f32 v29, v29, v32
	v_log_f32_e32 v29, v29
	v_add_f32_e32 v31, 1.0, v31
	v_sub_f32_e32 v28, -0.5, v28
	v_mul_f32_e32 v28, 0x3fb8aa3b, v28
	v_mul_f32_e32 v32, 0x3f317217, v29
	v_fma_f32 v32, v29, s27, -v32
	v_fmac_f32_e32 v32, 0x3377d1cf, v29
	v_fmac_f32_e32 v32, 0x3f317217, v29
	v_cmp_lt_f32_e64 s[4:5], |v29|, s38
	v_exp_f32_e32 v28, v28
	s_nop 0
	v_cndmask_b32_e64 v29, v29, v32, s[4:5]
	v_cndmask_b32_e32 v32, 0, v252, vcc
	v_cmp_gt_f32_e32 vcc, s26, v30
	v_sub_f32_e32 v29, v29, v32
	v_sub_f32_e32 v29, -0.5, v29
	v_cndmask_b32_e64 v32, 0, 32, vcc
	v_ldexp_f32 v30, v30, v32
	v_log_f32_e32 v30, v30
	v_mul_f32_e32 v29, 0x3fb8aa3b, v29
	v_exp_f32_e32 v29, v29
	v_mul_f32_e32 v28, 0xbfb8aa3b, v28
	v_mul_f32_e32 v32, 0x3f317217, v30
	v_fma_f32 v32, v30, s27, -v32
	v_fmac_f32_e32 v32, 0x3377d1cf, v30
	v_fmac_f32_e32 v32, 0x3f317217, v30
	v_cmp_lt_f32_e64 s[4:5], |v30|, s38
	v_mul_f32_e32 v29, 0xbfb8aa3b, v29
	v_exp_f32_e32 v28, v28
	v_cndmask_b32_e64 v30, v30, v32, s[4:5]
	v_cndmask_b32_e32 v32, 0, v252, vcc
	v_cmp_gt_f32_e32 vcc, s26, v31
	v_sub_f32_e32 v30, v30, v32
	v_sub_f32_e32 v30, -0.5, v30
	v_cndmask_b32_e64 v32, 0, 32, vcc
	v_ldexp_f32 v31, v31, v32
	v_log_f32_e32 v31, v31
	v_mul_f32_e32 v30, 0x3fb8aa3b, v30
	v_exp_f32_e32 v30, v30
	v_exp_f32_e32 v29, v29
	v_mul_f32_e32 v32, 0x3f317217, v31
	v_fma_f32 v32, v31, s27, -v32
	v_fmac_f32_e32 v32, 0x3377d1cf, v31
	v_fmac_f32_e32 v32, 0x3f317217, v31
	v_cmp_lt_f32_e64 s[4:5], |v31|, s38
	v_mul_f32_e32 v30, 0xbfb8aa3b, v30
	v_exp_f32_e32 v30, v30
	v_cndmask_b32_e64 v31, v31, v32, s[4:5]
	v_cndmask_b32_e32 v32, 0, v252, vcc
	v_sub_f32_e32 v31, v31, v32
	v_sub_f32_e32 v31, -0.5, v31
	v_mul_f32_e32 v31, 0x3fb8aa3b, v31
	v_exp_f32_e32 v31, v31
	s_nop 0
	v_mul_f32_e32 v31, 0xbfb8aa3b, v31
	v_exp_f32_e32 v31, v31
	ds_write_b128 v0, v[28:31] offset:64
	v_mov_b64_e32 v[28:29], v[148:149]
	v_mov_b64_e32 v[30:31], v[150:151]
	s_waitcnt vmcnt(0)
; #define LAS __attribute__((address_space(3)))
; DI void rwkv_scan_item(int j, int item, LAS unsigned char* lds) {
;     ...
;                   for (int nt = 0; nt < 4; ++nt) { const int ch = nt * 16 + fq * 4; f32x4 o;
; #pragma unroll
;                       for (int e = 0; e < 4; ++e) { const float wp = w0[ch + e] + acc[nt][e]; const float wl = -__logf(1.f + __expf(-wp)) - 0.5f; o[e] = __expf(-__expf(wl)); }
;                       *(LAS f32x4*)(sbuf + (r0 + fr) * 384 + ch) = o; } }
	v_add_f32_e32 v24, v24, v28
	v_mul_f32_e32 v24, 0xbfb8aa3b, v24
	v_exp_f32_e32 v24, v24
	v_add_f32_e32 v25, v25, v29
	v_mul_f32_e32 v25, 0xbfb8aa3b, v25
	v_exp_f32_e32 v25, v25
	v_add_f32_e32 v24, 1.0, v24
	v_cmp_gt_f32_e32 vcc, s26, v24
	v_add_f32_e32 v26, v26, v30
	v_add_f32_e32 v25, 1.0, v25
	v_cndmask_b32_e64 v28, 0, 32, vcc
	v_ldexp_f32 v24, v24, v28
	v_log_f32_e32 v24, v24
	v_mul_f32_e32 v26, 0xbfb8aa3b, v26
	v_exp_f32_e32 v26, v26
	v_add_f32_e32 v27, v27, v31
	v_mul_f32_e32 v28, 0x3f317217, v24
	v_fma_f32 v28, v24, s27, -v28
	v_fmac_f32_e32 v28, 0x3377d1cf, v24
	v_fmac_f32_e32 v28, 0x3f317217, v24
	v_cmp_lt_f32_e64 s[4:5], |v24|, s38
	v_add_f32_e32 v26, 1.0, v26
	v_mul_f32_e32 v27, 0xbfb8aa3b, v27
	v_cndmask_b32_e64 v24, v24, v28, s[4:5]
	v_cndmask_b32_e32 v28, 0, v252, vcc
	v_cmp_gt_f32_e32 vcc, s26, v25
	v_sub_f32_e32 v24, v24, v28
	v_exp_f32_e32 v27, v27
	v_cndmask_b32_e64 v28, 0, 32, vcc
	v_ldexp_f32 v25, v25, v28
	v_log_f32_e32 v25, v25
	v_add_f32_e32 v27, 1.0, v27
	v_sub_f32_e32 v24, -0.5, v24
	v_mul_f32_e32 v24, 0x3fb8aa3b, v24
	v_mul_f32_e32 v28, 0x3f317217, v25
	v_fma_f32 v28, v25, s27, -v28
	v_fmac_f32_e32 v28, 0x3377d1cf, v25
	v_fmac_f32_e32 v28, 0x3f317217, v25
	v_cmp_lt_f32_e64 s[4:5], |v25|, s38
	v_exp_f32_e32 v24, v24
	s_nop 0
	v_cndmask_b32_e64 v25, v25, v28, s[4:5]
	v_cndmask_b32_e32 v28, 0, v252, vcc
	v_cmp_gt_f32_e32 vcc, s26, v26
	v_sub_f32_e32 v25, v25, v28
	v_sub_f32_e32 v25, -0.5, v25
	v_cndmask_b32_e64 v28, 0, 32, vcc
	v_ldexp_f32 v26, v26, v28
	v_log_f32_e32 v26, v26
	v_mul_f32_e32 v25, 0x3fb8aa3b, v25
	v_exp_f32_e32 v25, v25
	v_mul_f32_e32 v24, 0xbfb8aa3b, v24
	v_mul_f32_e32 v28, 0x3f317217, v26
	v_fma_f32 v28, v26, s27, -v28
	v_fmac_f32_e32 v28, 0x3377d1cf, v26
	v_fmac_f32_e32 v28, 0x3f317217, v26
	v_cmp_lt_f32_e64 s[4:5], |v26|, s38
	v_mul_f32_e32 v25, 0xbfb8aa3b, v25
	v_exp_f32_e32 v24, v24
	v_cndmask_b32_e64 v26, v26, v28, s[4:5]
	v_cndmask_b32_e32 v28, 0, v252, vcc
	v_cmp_gt_f32_e32 vcc, s26, v27
	v_sub_f32_e32 v26, v26, v28
	v_sub_f32_e32 v26, -0.5, v26
	v_cndmask_b32_e64 v28, 0, 32, vcc
	v_ldexp_f32 v27, v27, v28
	v_log_f32_e32 v27, v27
	v_mul_f32_e32 v26, 0x3fb8aa3b, v26
	v_exp_f32_e32 v26, v26
	v_exp_f32_e32 v25, v25
	v_mul_f32_e32 v28, 0x3f317217, v27
	v_fma_f32 v28, v27, s27, -v28
	v_fmac_f32_e32 v28, 0x3377d1cf, v27
	v_fmac_f32_e32 v28, 0x3f317217, v27
	v_cmp_lt_f32_e64 s[4:5], |v27|, s38
	v_mul_f32_e32 v26, 0xbfb8aa3b, v26
	v_exp_f32_e32 v26, v26
	v_cndmask_b32_e64 v27, v27, v28, s[4:5]
	v_cndmask_b32_e32 v28, 0, v252, vcc
	v_sub_f32_e32 v27, v27, v28
	v_sub_f32_e32 v27, -0.5, v27
	v_mul_f32_e32 v27, 0x3fb8aa3b, v27
	v_exp_f32_e32 v27, v27
	s_nop 0
	v_mul_f32_e32 v27, 0xbfb8aa3b, v27
	v_exp_f32_e32 v27, v27
	ds_write_b128 v0, v[24:27] offset:128
	v_mov_b64_e32 v[24:25], v[152:153]
	v_mov_b64_e32 v[26:27], v[154:155]
	s_waitcnt vmcnt(0)
	v_add_f32_e32 v20, v20, v24
	v_mul_f32_e32 v20, 0xbfb8aa3b, v20
	v_exp_f32_e32 v20, v20
	v_add_f32_e32 v21, v21, v25
	v_mul_f32_e32 v21, 0xbfb8aa3b, v21
	v_exp_f32_e32 v21, v21
	v_add_f32_e32 v20, 1.0, v20
	v_cmp_gt_f32_e32 vcc, s26, v20
	v_add_f32_e32 v22, v22, v26
	v_add_f32_e32 v21, 1.0, v21
	v_cndmask_b32_e64 v24, 0, 32, vcc
	v_ldexp_f32 v20, v20, v24
	v_log_f32_e32 v20, v20
	v_mul_f32_e32 v22, 0xbfb8aa3b, v22
	v_exp_f32_e32 v22, v22
	v_add_f32_e32 v23, v23, v27
	v_mul_f32_e32 v24, 0x3f317217, v20
	v_fma_f32 v24, v20, s27, -v24
	v_fmac_f32_e32 v24, 0x3377d1cf, v20
	v_fmac_f32_e32 v24, 0x3f317217, v20
	v_cmp_lt_f32_e64 s[4:5], |v20|, s38
	v_add_f32_e32 v22, 1.0, v22
	v_mul_f32_e32 v23, 0xbfb8aa3b, v23
	v_cndmask_b32_e64 v20, v20, v24, s[4:5]
	v_cndmask_b32_e32 v24, 0, v252, vcc
	v_cmp_gt_f32_e32 vcc, s26, v21
	v_sub_f32_e32 v20, v20, v24
	v_exp_f32_e32 v23, v23
	v_cndmask_b32_e64 v24, 0, 32, vcc
	v_ldexp_f32 v21, v21, v24
	v_log_f32_e32 v21, v21
	v_add_f32_e32 v23, 1.0, v23
	v_sub_f32_e32 v20, -0.5, v20
	v_mul_f32_e32 v20, 0x3fb8aa3b, v20
	v_mul_f32_e32 v24, 0x3f317217, v21
	v_fma_f32 v24, v21, s27, -v24
	v_fmac_f32_e32 v24, 0x3377d1cf, v21
	v_fmac_f32_e32 v24, 0x3f317217, v21
	v_cmp_lt_f32_e64 s[4:5], |v21|, s38
	v_exp_f32_e32 v20, v20
	s_nop 0
	v_cndmask_b32_e64 v21, v21, v24, s[4:5]
	v_cndmask_b32_e32 v24, 0, v252, vcc
	v_cmp_gt_f32_e32 vcc, s26, v22
	v_sub_f32_e32 v21, v21, v24
	v_sub_f32_e32 v21, -0.5, v21
	v_cndmask_b32_e64 v24, 0, 32, vcc
	v_ldexp_f32 v22, v22, v24
	v_log_f32_e32 v22, v22
	v_mul_f32_e32 v21, 0x3fb8aa3b, v21
	v_exp_f32_e32 v21, v21
	v_mul_f32_e32 v20, 0xbfb8aa3b, v20
	v_mul_f32_e32 v24, 0x3f317217, v22
	v_fma_f32 v24, v22, s27, -v24
	v_fmac_f32_e32 v24, 0x3377d1cf, v22
	v_fmac_f32_e32 v24, 0x3f317217, v22
	v_cmp_lt_f32_e64 s[4:5], |v22|, s38
	v_mul_f32_e32 v21, 0xbfb8aa3b, v21
	v_exp_f32_e32 v20, v20
	v_cndmask_b32_e64 v22, v22, v24, s[4:5]
	v_cndmask_b32_e32 v24, 0, v252, vcc
	v_cmp_gt_f32_e32 vcc, s26, v23
	v_sub_f32_e32 v22, v22, v24
	v_sub_f32_e32 v22, -0.5, v22
	v_cndmask_b32_e64 v24, 0, 32, vcc
	v_ldexp_f32 v23, v23, v24
	v_log_f32_e32 v23, v23
	v_mul_f32_e32 v22, 0x3fb8aa3b, v22
	v_exp_f32_e32 v22, v22
	v_exp_f32_e32 v21, v21
	v_mul_f32_e32 v24, 0x3f317217, v23
	v_fma_f32 v24, v23, s27, -v24
	v_fmac_f32_e32 v24, 0x3377d1cf, v23
	v_fmac_f32_e32 v24, 0x3f317217, v23
	v_cmp_lt_f32_e64 s[4:5], |v23|, s38
	v_mul_f32_e32 v22, 0xbfb8aa3b, v22
	v_exp_f32_e32 v22, v22
	v_cndmask_b32_e64 v23, v23, v24, s[4:5]
	v_cndmask_b32_e32 v24, 0, v252, vcc
	v_sub_f32_e32 v23, v23, v24
	v_sub_f32_e32 v23, -0.5, v23
	v_mul_f32_e32 v23, 0x3fb8aa3b, v23
	v_exp_f32_e32 v23, v23
	s_add_u32 s4, s2, s28
	s_addc_u32 s5, s3, 0
	s_lshl_b32 s18, s21, 2
	v_mul_f32_e32 v23, 0xbfb8aa3b, v23
	v_exp_f32_e32 v23, v23
	ds_write_b128 v0, v[20:23] offset:192
	s_branch .LBB0_126
; #define LAS __attribute__((address_space(3)))
; #define IN(k) ((const float*)kload(8 * (k)))
; DI float sigmoidf_(float x) { return 1.f / (1.f + __expf(-x)); }
; DI int tok_of(int d, int i) { if (i < LC) return d ? (LC - 1 - i) : i; return d ? (LC + SL - 1 - (i - LC)) : i; }
; DI void rwkv_scan_item(int j, int item, LAS unsigned char* lds) {
;     ...
;                 { f32x4 acc[4];
; #pragma unroll
;                   for (int i = 0; i < 4; ++i) acc[i] = (f32x4){0.f, 0.f, 0.f, 0.f};
;                   mm16<4, 2>(Lw + 64, 136, W2a, 72, acc, fr, fq);
; #pragma unroll
;                   for (int nt = 0; nt < 4; ++nt) { const int ch = nt * 16 + fq * 4; f32x4 o;
; #pragma unroll
;                       for (int e = 0; e < 4; ++e) o[e] = sigmoidf_(a0[ch + e] + acc[nt][e]);
;                       *(LAS f32x4*)(sbuf + (r0 + fr) * 384 + 128 + ch) = o; } }
;                 asm volatile("s_waitcnt lgkmcnt(0)" ::: "memory");
;                 const float* kkw = IN(28) + j * D + head * 64; const float* kaw = IN(29) + j * D + head * 64; const float* rkw = IN(30) + (j * 16 + head) * 64;
; #pragma unroll
;                 for (int i = 0; i < 4; ++i) {
;                     const int row = r0 + i * 4 + fq, ch = fr * 4; const size_t mr = (size_t)b * T + tok_of(d, i0 + row);
;                     const u32x2 ku = kv[i], ru = rv[i], vu = vv[i];
;                     const float kf[4] = {bflo(ku.x), bfhi(ku.x), bflo(ku.y), bfhi(ku.y)}, rf[4] = {bflo(ru.x), bfhi(ru.x), bflo(ru.y), bfhi(ru.y)}, vf[4] = {bflo(vu.x), bfhi(vu.x), bflo(vu.y), bfhi(vu.y)};
.Lprep_af:
	v_add3_u32 v0, s35, v84, v107
	ds_read_b128 v[20:23], v83 offset:128
	ds_read_b128 v[24:27], v108
	ds_read_b128 v[28:31], v108 offset:2304
	ds_read_b128 v[32:35], v108 offset:4608
	ds_read_b128 v[74:77], v108 offset:6912
	s_waitcnt lgkmcnt(3)
	v_mfma_f32_16x16x32_bf16 v[24:27], v[24:27], v[20:23], 0
	s_waitcnt lgkmcnt(2)
	v_mfma_f32_16x16x32_bf16 v[28:31], v[28:31], v[20:23], 0
	s_waitcnt lgkmcnt(1)
	v_mfma_f32_16x16x32_bf16 v[32:35], v[32:35], v[20:23], 0
	s_waitcnt lgkmcnt(0)
	v_mfma_f32_16x16x32_bf16 v[20:23], v[74:77], v[20:23], 0
	ds_read_b128 v[74:77], v83 offset:192
	ds_read_b128 v[110:113], v108 offset:64
	s_waitcnt lgkmcnt(0)
	v_mfma_f32_16x16x32_bf16 v[110:113], v[110:113], v[74:77], v[24:27]
	s_nop 2
	ds_read_b128 v[24:27], v108 offset:2368
	s_waitcnt lgkmcnt(0)
	v_mfma_f32_16x16x32_bf16 v[28:31], v[24:27], v[74:77], v[28:31]
	ds_read_b128 v[24:27], v108 offset:4672
	s_waitcnt lgkmcnt(0)
	v_mfma_f32_16x16x32_bf16 v[24:27], v[24:27], v[74:77], v[32:35]
	s_nop 2
	ds_read_b128 v[32:35], v108 offset:6976
	s_waitcnt lgkmcnt(0)
	v_mfma_f32_16x16x32_bf16 v[20:23], v[32:35], v[74:77], v[20:23]
	v_mov_b64_e32 v[32:33], v[156:157]
	v_mov_b64_e32 v[34:35], v[158:159]
	s_waitcnt vmcnt(0)
	v_add_f32_e32 v34, v112, v34
	v_add_f32_e32 v35, v113, v35
	v_mul_f32_e32 v34, 0xbfb8aa3b, v34
	v_mul_f32_e32 v35, 0xbfb8aa3b, v35
	v_exp_f32_e32 v34, v34
	v_exp_f32_e32 v35, v35
	v_add_f32_e32 v32, v110, v32
	v_add_f32_e32 v33, v111, v33
	v_mul_f32_e32 v32, 0xbfb8aa3b, v32
	v_pk_add_f32 v[34:35], v[34:35], 1.0 op_sel_hi:[1,0]
	v_mul_f32_e32 v33, 0xbfb8aa3b, v33
	v_div_scale_f32 v38, s[2:3], v35, v35, 1.0
	v_rcp_f32_e32 v39, v38
	v_exp_f32_e32 v32, v32
	v_exp_f32_e32 v33, v33
	v_fma_f32 v74, -v38, v39, 1.0
	v_fmac_f32_e32 v39, v74, v39
	v_div_scale_f32 v74, vcc, 1.0, v35, 1.0
	v_mul_f32_e32 v75, v74, v39
	v_fma_f32 v76, -v38, v75, v74
	v_fmac_f32_e32 v75, v76, v39
	v_fma_f32 v38, -v38, v75, v74
	v_div_fmas_f32 v38, v38, v39, v75
	v_div_fixup_f32 v35, v38, v35, 1.0
	v_div_scale_f32 v38, s[2:3], v34, v34, 1.0
	v_rcp_f32_e32 v39, v38
	v_pk_add_f32 v[32:33], v[32:33], 1.0 op_sel_hi:[1,0]
	v_fma_f32 v74, -v38, v39, 1.0
	v_fmac_f32_e32 v39, v74, v39
	v_div_scale_f32 v74, vcc, 1.0, v34, 1.0
	v_mul_f32_e32 v75, v74, v39
	v_fma_f32 v76, -v38, v75, v74
	v_fmac_f32_e32 v75, v76, v39
	v_fma_f32 v38, -v38, v75, v74
	v_div_fmas_f32 v38, v38, v39, v75
	v_div_fixup_f32 v34, v38, v34, 1.0
	v_div_scale_f32 v38, s[2:3], v33, v33, 1.0
	v_rcp_f32_e32 v39, v38
	s_nop 0
	v_fma_f32 v74, -v38, v39, 1.0
	v_fmac_f32_e32 v39, v74, v39
	v_div_scale_f32 v74, vcc, 1.0, v33, 1.0
	v_mul_f32_e32 v75, v74, v39
	v_fma_f32 v76, -v38, v75, v74
	v_fmac_f32_e32 v75, v76, v39
	v_fma_f32 v38, -v38, v75, v74
	v_div_fmas_f32 v38, v38, v39, v75
	v_div_fixup_f32 v33, v38, v33, 1.0
	v_div_scale_f32 v38, s[2:3], v32, v32, 1.0
	v_rcp_f32_e32 v39, v38
	s_nop 0
	v_fma_f32 v74, -v38, v39, 1.0
	v_fmac_f32_e32 v39, v74, v39
	v_div_scale_f32 v74, vcc, 1.0, v32, 1.0
	v_mul_f32_e32 v75, v74, v39
	v_fma_f32 v76, -v38, v75, v74
	v_fmac_f32_e32 v75, v76, v39
	v_fma_f32 v38, -v38, v75, v74
	v_div_fmas_f32 v38, v38, v39, v75
	v_div_fixup_f32 v32, v38, v32, 1.0
	ds_write_b128 v0, v[32:35] offset:512
	v_mov_b64_e32 v[32:33], v[160:161]
	v_mov_b64_e32 v[34:35], v[162:163]
	v_and_b32_e32 v39, 0xffff0000, v40
	s_waitcnt vmcnt(0)
	v_add_f32_e32 v30, v30, v34
	v_add_f32_e32 v31, v31, v35
	v_mul_f32_e32 v30, 0xbfb8aa3b, v30
	v_mul_f32_e32 v31, 0xbfb8aa3b, v31
	v_exp_f32_e32 v30, v30
	v_exp_f32_e32 v31, v31
	v_add_f32_e32 v28, v28, v32
	v_add_f32_e32 v29, v29, v33
	v_mul_f32_e32 v28, 0xbfb8aa3b, v28
	v_pk_add_f32 v[30:31], v[30:31], 1.0 op_sel_hi:[1,0]
	v_mul_f32_e32 v29, 0xbfb8aa3b, v29
	v_div_scale_f32 v32, s[2:3], v31, v31, 1.0
	v_rcp_f32_e32 v33, v32
	v_exp_f32_e32 v28, v28
	v_exp_f32_e32 v29, v29
	v_fma_f32 v34, -v32, v33, 1.0
	v_fmac_f32_e32 v33, v34, v33
	v_div_scale_f32 v34, vcc, 1.0, v31, 1.0
	v_mul_f32_e32 v35, v34, v33
	v_fma_f32 v38, -v32, v35, v34
	v_fmac_f32_e32 v35, v38, v33
	v_fma_f32 v32, -v32, v35, v34
	v_div_fmas_f32 v32, v32, v33, v35
	v_div_fixup_f32 v31, v32, v31, 1.0
	v_div_scale_f32 v32, s[2:3], v30, v30, 1.0
	v_rcp_f32_e32 v33, v32
	v_pk_add_f32 v[28:29], v[28:29], 1.0 op_sel_hi:[1,0]
	v_fma_f32 v34, -v32, v33, 1.0
	v_fmac_f32_e32 v33, v34, v33
	v_div_scale_f32 v34, vcc, 1.0, v30, 1.0
	v_mul_f32_e32 v35, v34, v33
	v_fma_f32 v38, -v32, v35, v34
	v_fmac_f32_e32 v35, v38, v33
	v_fma_f32 v32, -v32, v35, v34
	v_div_fmas_f32 v32, v32, v33, v35
	v_div_fixup_f32 v30, v32, v30, 1.0
	v_div_scale_f32 v32, s[2:3], v29, v29, 1.0
	v_rcp_f32_e32 v33, v32
	s_nop 0
	v_fma_f32 v34, -v32, v33, 1.0
	v_fmac_f32_e32 v33, v34, v33
	v_div_scale_f32 v34, vcc, 1.0, v29, 1.0
	v_mul_f32_e32 v35, v34, v33
	v_fma_f32 v38, -v32, v35, v34
	v_fmac_f32_e32 v35, v38, v33
	v_fma_f32 v32, -v32, v35, v34
	v_div_fmas_f32 v32, v32, v33, v35
	v_div_fixup_f32 v29, v32, v29, 1.0
	v_div_scale_f32 v32, s[2:3], v28, v28, 1.0
	v_rcp_f32_e32 v33, v32
	s_nop 0
	v_fma_f32 v34, -v32, v33, 1.0
	v_fmac_f32_e32 v33, v34, v33
	v_div_scale_f32 v34, vcc, 1.0, v28, 1.0
	v_mul_f32_e32 v35, v34, v33
	v_fma_f32 v38, -v32, v35, v34
	v_fmac_f32_e32 v35, v38, v33
	v_fma_f32 v32, -v32, v35, v34
	v_div_fmas_f32 v32, v32, v33, v35
	v_div_fixup_f32 v28, v32, v28, 1.0
	ds_write_b128 v0, v[28:31] offset:576
	v_mov_b64_e32 v[28:29], v[164:165]
	v_mov_b64_e32 v[30:31], v[166:167]
	v_lshlrev_b32_e32 v34, 16, v36
	v_and_b32_e32 v35, 0xffff0000, v36
	v_lshlrev_b32_e32 v36, 16, v37
	v_and_b32_e32 v37, 0xffff0000, v37
	v_lshlrev_b32_e32 v38, 16, v40
	v_lshlrev_b32_e32 v40, 16, v41
	v_and_b32_e32 v41, 0xffff0000, v41
	s_waitcnt vmcnt(0)
; #define LAS __attribute__((address_space(3)))
; DI float sigmoidf_(float x) { return 1.f / (1.f + __expf(-x)); }
; DI void rwkv_scan_item(int j, int item, LAS unsigned char* lds) {
;     ...
;                   for (int nt = 0; nt < 4; ++nt) { const int ch = nt * 16 + fq * 4; f32x4 o;
; #pragma unroll
;                       for (int e = 0; e < 4; ++e) o[e] = sigmoidf_(a0[ch + e] + acc[nt][e]);
;                       *(LAS f32x4*)(sbuf + (r0 + fr) * 384 + 128 + ch) = o; } }
	v_add_f32_e32 v26, v26, v30
	v_add_f32_e32 v27, v27, v31
	v_mul_f32_e32 v26, 0xbfb8aa3b, v26
	v_mul_f32_e32 v27, 0xbfb8aa3b, v27
	v_exp_f32_e32 v26, v26
	v_exp_f32_e32 v27, v27
	v_add_f32_e32 v24, v24, v28
	v_add_f32_e32 v25, v25, v29
	v_mul_f32_e32 v24, 0xbfb8aa3b, v24
	v_pk_add_f32 v[26:27], v[26:27], 1.0 op_sel_hi:[1,0]
	v_mul_f32_e32 v25, 0xbfb8aa3b, v25
	v_div_scale_f32 v28, s[2:3], v27, v27, 1.0
	v_rcp_f32_e32 v29, v28
	v_exp_f32_e32 v24, v24
	v_exp_f32_e32 v25, v25
	v_fma_f32 v30, -v28, v29, 1.0
	v_fmac_f32_e32 v29, v30, v29
	v_div_scale_f32 v30, vcc, 1.0, v27, 1.0
	v_mul_f32_e32 v31, v30, v29
	v_fma_f32 v32, -v28, v31, v30
	v_fmac_f32_e32 v31, v32, v29
	v_fma_f32 v28, -v28, v31, v30
	v_div_fmas_f32 v28, v28, v29, v31
	v_div_fixup_f32 v27, v28, v27, 1.0
	v_div_scale_f32 v28, s[2:3], v26, v26, 1.0
	v_rcp_f32_e32 v29, v28
	v_pk_add_f32 v[24:25], v[24:25], 1.0 op_sel_hi:[1,0]
	v_fma_f32 v30, -v28, v29, 1.0
	v_fmac_f32_e32 v29, v30, v29
	v_div_scale_f32 v30, vcc, 1.0, v26, 1.0
	v_mul_f32_e32 v31, v30, v29
	v_fma_f32 v32, -v28, v31, v30
	v_fmac_f32_e32 v31, v32, v29
	v_fma_f32 v28, -v28, v31, v30
	v_div_fmas_f32 v28, v28, v29, v31
	v_div_fixup_f32 v26, v28, v26, 1.0
	v_div_scale_f32 v28, s[2:3], v25, v25, 1.0
	v_rcp_f32_e32 v29, v28
	s_nop 0
	v_fma_f32 v30, -v28, v29, 1.0
	v_fmac_f32_e32 v29, v30, v29
	v_div_scale_f32 v30, vcc, 1.0, v25, 1.0
	v_mul_f32_e32 v31, v30, v29
	v_fma_f32 v32, -v28, v31, v30
	v_fmac_f32_e32 v31, v32, v29
	v_fma_f32 v28, -v28, v31, v30
	v_div_fmas_f32 v28, v28, v29, v31
	v_div_fixup_f32 v25, v28, v25, 1.0
	v_div_scale_f32 v28, s[2:3], v24, v24, 1.0
	v_rcp_f32_e32 v29, v28
	s_nop 0
	v_fma_f32 v30, -v28, v29, 1.0
	v_fmac_f32_e32 v29, v30, v29
	v_div_scale_f32 v30, vcc, 1.0, v24, 1.0
	v_mul_f32_e32 v31, v30, v29
	v_fma_f32 v32, -v28, v31, v30
	v_fmac_f32_e32 v31, v32, v29
	v_fma_f32 v28, -v28, v31, v30
	v_div_fmas_f32 v28, v28, v29, v31
	v_div_fixup_f32 v24, v28, v24, 1.0
	ds_write_b128 v0, v[24:27] offset:640
	v_mov_b64_e32 v[24:25], v[168:169]
	v_mov_b64_e32 v[26:27], v[170:171]
	s_mov_b64 s[4:5], s[36:37]
	v_and_b32_e32 v29, 0xffff0000, v72
	s_waitcnt vmcnt(0)
	v_add_f32_e32 v22, v22, v26
	v_add_f32_e32 v23, v23, v27
	v_mul_f32_e32 v22, 0xbfb8aa3b, v22
	v_mul_f32_e32 v23, 0xbfb8aa3b, v23
	v_exp_f32_e32 v22, v22
	v_exp_f32_e32 v23, v23
	v_add_f32_e32 v20, v20, v24
	v_add_f32_e32 v21, v21, v25
	v_mul_f32_e32 v20, 0xbfb8aa3b, v20
	v_pk_add_f32 v[22:23], v[22:23], 1.0 op_sel_hi:[1,0]
	v_mul_f32_e32 v21, 0xbfb8aa3b, v21
	v_div_scale_f32 v24, s[2:3], v23, v23, 1.0
	v_rcp_f32_e32 v25, v24
	v_exp_f32_e32 v20, v20
	v_exp_f32_e32 v21, v21
	v_fma_f32 v26, -v24, v25, 1.0
	v_fmac_f32_e32 v25, v26, v25
	v_div_scale_f32 v26, vcc, 1.0, v23, 1.0
	v_mul_f32_e32 v27, v26, v25
	v_fma_f32 v28, -v24, v27, v26
	v_fmac_f32_e32 v27, v28, v25
	v_fma_f32 v24, -v24, v27, v26
	v_div_fmas_f32 v24, v24, v25, v27
	v_div_fixup_f32 v23, v24, v23, 1.0
	v_div_scale_f32 v24, s[2:3], v22, v22, 1.0
	v_rcp_f32_e32 v25, v24
	v_pk_add_f32 v[20:21], v[20:21], 1.0 op_sel_hi:[1,0]
	v_fma_f32 v26, -v24, v25, 1.0
	v_fmac_f32_e32 v25, v26, v25
	v_div_scale_f32 v26, vcc, 1.0, v22, 1.0
	v_mul_f32_e32 v27, v26, v25
	v_fma_f32 v28, -v24, v27, v26
	v_fmac_f32_e32 v27, v28, v25
	v_fma_f32 v24, -v24, v27, v26
	v_div_fmas_f32 v24, v24, v25, v27
	v_div_fixup_f32 v22, v24, v22, 1.0
	v_div_scale_f32 v24, s[2:3], v21, v21, 1.0
	v_rcp_f32_e32 v25, v24
	s_nop 0
	v_fma_f32 v26, -v24, v25, 1.0
	v_fmac_f32_e32 v25, v26, v25
	v_div_scale_f32 v26, vcc, 1.0, v21, 1.0
	v_mul_f32_e32 v27, v26, v25
	v_fma_f32 v28, -v24, v27, v26
	v_fmac_f32_e32 v27, v28, v25
	v_fma_f32 v24, -v24, v27, v26
	v_div_fmas_f32 v24, v24, v25, v27
	v_div_fixup_f32 v21, v24, v21, 1.0
	v_div_scale_f32 v24, s[2:3], v20, v20, 1.0
	v_rcp_f32_e32 v25, v24
	s_mov_b64 s[2:3], s[36:37]
	v_fma_f32 v26, -v24, v25, 1.0
	v_fmac_f32_e32 v25, v26, v25
	v_div_scale_f32 v26, vcc, 1.0, v20, 1.0
	v_mul_f32_e32 v27, v26, v25
	v_fma_f32 v28, -v24, v27, v26
	v_fmac_f32_e32 v27, v28, v25
	v_fma_f32 v24, -v24, v27, v26
	v_div_fmas_f32 v24, v24, v25, v27
	v_div_fixup_f32 v20, v24, v20, 1.0
	ds_write_b128 v0, v[20:23] offset:704
	s_waitcnt lgkmcnt(0)
; #define LAS __attribute__((address_space(3)))
; #define IN(k) ((const float*)kload(8 * (k)))
; DI float red16(float x) { x += dppmov<0xB1>(x); x += dppmov<0x4E>(x); x += dppmov<0x141>(x); x += dppmov<0x140>(x); return x; }
; DI int tok_of(int d, int i) { if (i < LC) return d ? (LC - 1 - i) : i; return d ? (LC + SL - 1 - (i - LC)) : i; }
; DI void rwkv_scan_item(int j, int item, LAS unsigned char* lds) {
;     ...
;                 const float* kkw = IN(28) + j * D + head * 64; const float* kaw = IN(29) + j * D + head * 64; const float* rkw = IN(30) + (j * 16 + head) * 64;
; #pragma unroll
;                 for (int i = 0; i < 4; ++i) {
;                     const int row = r0 + i * 4 + fq, ch = fr * 4; const size_t mr = (size_t)b * T + tok_of(d, i0 + row);
;                     const u32x2 ku = kv[i], ru = rv[i], vu = vv[i];
;                     const float kf[4] = {bflo(ku.x), bfhi(ku.x), bflo(ku.y), bfhi(ku.y)}, rf[4] = {bflo(ru.x), bfhi(ru.x), bflo(ru.y), bfhi(ru.y)}, vf[4] = {bflo(vu.x), bfhi(vu.x), bflo(vu.y), bfhi(vu.y)};
;                     LAS float* st = sbuf + row * 384;
;                     const f32x4 as = *(const LAS f32x4*)(st + 128 + ch);
;                     float kk[4], kd[4]; float ss = 0.f, bon = 0.f;
; #pragma unroll
;                     for (int e = 0; e < 4; ++e) { kk[e] = kf[e] * kkw[ch + e]; ss += kk[e] * kk[e]; kd[e] = kf[e] * (1.f + (as[e] - 1.f) * kaw[ch + e]); bon += rf[e] * kd[e] * rkw[ch + e]; }
;                     ss = red16(ss); bon = red16(bon);
;                     const float rn = rsqrtf(fmaxf(ss, 1e-24f));
;                     f32x4 okd, oa, ob, orr, ov;
; #pragma unroll
;                     for (int e = 0; e < 4; ++e) { const float kn = kk[e] * rn; okd[e] = kd[e]; oa[e] = -kn; ob[e] = kn * as[e]; orr[e] = rf[e]; ov[e] = vf[e]; }
;                     *(LAS f32x4*)(st + 64 + ch) = okd; *(LAS f32x4*)(st + 128 + ch) = oa; *(LAS f32x4*)(st + 192 + ch) = ob; *(LAS f32x4*)(st + 256 + ch) = orr; *(LAS f32x4*)(st + 320 + ch) = ov;
;                     if (fr == 0) SB[mr * 16 + head] = bon;
	v_lshlrev_b32_e32 v0, 2, v42
	v_add3_u32 v109, s35, v95, v0
	s_waitcnt lgkmcnt(0)
	s_add_u32 s2, s2, s18
	s_addc_u32 s3, s3, 0
	s_add_u32 s2, s2, s28
	s_addc_u32 s3, s3, 0
	s_add_u32 s4, s4, s18
	s_mov_b64 s[18:19], s[36:37]
	s_addc_u32 s5, s5, 0
	s_add_u32 s4, s4, s28
	s_addc_u32 s5, s5, 0
	v_mov_b64_e32 v[30:31], v[172:173]
	v_mov_b64_e32 v[32:33], v[174:175]
	v_mov_b64_e32 v[20:21], v[176:177]
	v_mov_b64_e32 v[22:23], v[178:179]
	s_waitcnt lgkmcnt(0)
	s_add_u32 s18, s18, s29
	s_addc_u32 s19, s19, 0
	v_mov_b64_e32 v[24:25], v[120:121]
	v_mov_b64_e32 v[26:27], v[122:123]
	ds_read_b128 v[110:113], v109 offset:512
	v_lshlrev_b32_e32 v28, 16, v72
	v_lshl_add_u64 v[74:75], s[2:3], 0, v[0:1]
	v_lshl_add_u64 v[76:77], s[4:5], 0, v[0:1]
	v_lshl_add_u64 v[78:79], s[18:19], 0, v[0:1]
	v_pk_mul_f32 v[114:115], v[30:31], v[28:29]
	s_waitcnt lgkmcnt(0)
	v_pk_add_f32 v[30:31], v[110:111], -1.0 op_sel_hi:[1,0]
	v_pk_mul_f32 v[116:117], v[114:115], v[114:115]
	v_pk_fma_f32 v[20:21], v[30:31], v[20:21], 1.0 op_sel_hi:[1,1,0]
	v_pk_add_f32 v[30:31], v[112:113], -1.0 op_sel_hi:[1,0]
	v_pk_mul_f32 v[28:29], v[20:21], v[28:29]
	v_and_b32_e32 v21, 0xffff0000, v73
	v_mul_f32_e32 v20, v28, v34
	v_fma_f32 v118, v24, v20, 0
	v_mul_f32_e32 v20, v29, v35
	v_fmac_f32_e32 v118, v25, v20
	v_lshlrev_b32_e32 v20, 16, v73
	v_pk_mul_f32 v[24:25], v[32:33], v[20:21]
	v_pk_fma_f32 v[30:31], v[30:31], v[22:23], 1.0 op_sel_hi:[1,1,0]
	v_pk_mul_f32 v[72:73], v[24:25], v[24:25]
	v_add_f32_e32 v116, v116, v117
	v_pk_mul_f32 v[30:31], v[30:31], v[20:21]
	v_add_f32_e32 v72, v116, v72
	v_mul_f32_e32 v20, v30, v36
	v_add_f32_e32 v72, v72, v73
	v_fmac_f32_e32 v118, v26, v20
	v_mul_f32_e32 v21, v31, v37
	v_add_f32_dpp v20, v72, v72 quad_perm:[1,0,3,2] row_mask:0xf bank_mask:0xf bound_ctrl:1
	v_fmac_f32_e32 v118, v27, v21
	s_nop 0
	v_add_f32_dpp v20, v20, v20 quad_perm:[2,3,0,1] row_mask:0xf bank_mask:0xf bound_ctrl:1
	s_nop 1
	v_add_f32_dpp v20, v20, v20 row_half_mirror row_mask:0xf bank_mask:0xf bound_ctrl:1
	s_nop 1
	v_add_f32_dpp v72, v20, v20 row_mirror row_mask:0xf bank_mask:0xf bound_ctrl:1
	v_max_f32_e32 v72, 0x179abe15, v72
	v_rsq_f32_e32 v72, v72
	v_add_f32_dpp v20, v118, v118 quad_perm:[1,0,3,2] row_mask:0xf bank_mask:0xf bound_ctrl:1
	v_pk_mul_f32 v[118:119], v[114:115], v[72:73] op_sel_hi:[1,0]
	s_nop 0
	v_add_f32_dpp v20, v20, v20 quad_perm:[2,3,0,1] row_mask:0xf bank_mask:0xf bound_ctrl:1
	v_pk_mul_f32 v[24:25], v[24:25], v[72:73] op_sel_hi:[1,0]
	v_xor_b32_e32 v115, 0x80000000, v119
	v_add_f32_dpp v20, v20, v20 row_half_mirror row_mask:0xf bank_mask:0xf bound_ctrl:1
	v_xor_b32_e32 v114, 0x80000000, v118
	v_xor_b32_e32 v116, 0x80000000, v24
	v_mov_b32_dpp v21, v20 row_mirror row_mask:0xf bank_mask:0xf bound_ctrl:1
	v_xor_b32_e32 v117, 0x80000000, v25
	v_pk_mul_f32 v[112:113], v[112:113], v[24:25]
	v_pk_mul_f32 v[110:111], v[110:111], v[118:119]
	ds_write_b128 v109, v[28:31] offset:256
	ds_write_b128 v109, v[114:117] offset:512
	ds_write_b128 v109, v[110:113] offset:768
	ds_write_b128 v109, v[34:37] offset:1024
	ds_write_b128 v109, v[38:41] offset:1280
	s_and_saveexec_b64 s[2:3], s[42:43]
	s_cbranch_execz .LBB0_119
	v_lshlrev_b64 v[22:23], 6, v[66:67]
	v_lshl_add_u64 v[22:23], s[14:15], 0, v[22:23]
	v_add_f32_e32 v20, v20, v21
	global_store_dword v[22:23], v20, off
	v_mov_b64_e32 v[32:33], v[174:175]
	s_nop 0
	v_mov_b64_e32 v[22:23], v[178:179]
	v_mov_b64_e32 v[26:27], v[122:123]
